# stagger: odd quads enter the per-quad stage chain ~7us late (2 x s_sleep 127 before S2), on top of v71
# speedup vs baseline: 1.0034x; 1.0034x over previous
.LBB0_785:
	s_or_b64 exec, exec, s[2:3]
	s_cmp_lt_i32 s88, 5
	s_cselect_b64 s[0:1], -1, 0
	s_cmp_gt_i32 s89, 4
	s_cselect_b64 s[2:3], -1, 0
	s_and_b64 s[0:1], s[0:1], s[2:3]
	s_andn2_b64 vcc, exec, s[0:1]
	s_cbranch_vccnz .LBB0_869
	s_bitcmp1_b32 s86, 2
	s_cbranch_scc0 .Lqstag_skip
	s_sleep 127
	s_sleep 127
